# P3 unit: bias-table and gate loads taken off the per-unit critical path; P0 GEMV reduction: bias loaded once, pointer load before the barriers
# speedup vs baseline: 1.0653x; 1.0067x over previous
.Lgk_nopf:
	s_waitcnt lgkmcnt(15)
	v_fmac_f32_e32 v47, v52, v228
	v_fmac_f32_e32 v47, v53, v229
	v_fmac_f32_e32 v47, v54, v230
	v_fmac_f32_e32 v47, v55, v231
	v_fmac_f32_e32 v46, v64, v228
	v_fmac_f32_e32 v46, v65, v229
	v_fmac_f32_e32 v46, v66, v230
	v_fmac_f32_e32 v46, v67, v231
	v_fmac_f32_e32 v45, v68, v228
	v_fmac_f32_e32 v45, v69, v229
	v_fmac_f32_e32 v45, v70, v230
	v_fmac_f32_e32 v45, v71, v231
	v_fmac_f32_e32 v44, v72, v228
	v_fmac_f32_e32 v44, v73, v229
	v_fmac_f32_e32 v44, v74, v230
	v_fmac_f32_e32 v44, v75, v231
	v_fmac_f32_e32 v43, v76, v228
	v_fmac_f32_e32 v43, v77, v229
	v_fmac_f32_e32 v43, v78, v230
	v_fmac_f32_e32 v43, v79, v231
	v_fmac_f32_e32 v42, v80, v228
	v_fmac_f32_e32 v42, v81, v229
	v_fmac_f32_e32 v42, v82, v230
	v_fmac_f32_e32 v42, v83, v231
	v_fmac_f32_e32 v41, v84, v228
	v_fmac_f32_e32 v41, v85, v229
	v_fmac_f32_e32 v41, v86, v230
	v_fmac_f32_e32 v41, v87, v231
	v_fmac_f32_e32 v40, v88, v228
	v_fmac_f32_e32 v40, v89, v229
	v_fmac_f32_e32 v40, v90, v230
	v_fmac_f32_e32 v40, v91, v231
	v_fmac_f32_e32 v39, v92, v228
	v_fmac_f32_e32 v39, v93, v229
	v_fmac_f32_e32 v39, v94, v230
	v_fmac_f32_e32 v39, v95, v231
	v_fmac_f32_e32 v38, v96, v228
	v_fmac_f32_e32 v38, v97, v229
	v_fmac_f32_e32 v38, v98, v230
	v_fmac_f32_e32 v38, v99, v231
	v_fmac_f32_e32 v37, v100, v228
	v_fmac_f32_e32 v37, v101, v229
	v_fmac_f32_e32 v37, v102, v230
	v_fmac_f32_e32 v37, v103, v231
	v_fmac_f32_e32 v36, v104, v228
	v_fmac_f32_e32 v36, v105, v229
	v_fmac_f32_e32 v36, v106, v230
	v_fmac_f32_e32 v36, v107, v231
	v_fmac_f32_e32 v35, v108, v228
	v_fmac_f32_e32 v35, v109, v229
	v_fmac_f32_e32 v35, v110, v230
	v_fmac_f32_e32 v35, v111, v231
	v_fmac_f32_e32 v34, v112, v228
	v_fmac_f32_e32 v34, v113, v229
	v_fmac_f32_e32 v34, v114, v230
	v_fmac_f32_e32 v34, v115, v231
	v_fmac_f32_e32 v33, v116, v228
	v_fmac_f32_e32 v33, v117, v229
	v_fmac_f32_e32 v33, v118, v230
	v_fmac_f32_e32 v33, v119, v231
	v_fmac_f32_e32 v32, v120, v228
	v_fmac_f32_e32 v32, v121, v229
	v_fmac_f32_e32 v32, v122, v230
	v_fmac_f32_e32 v32, v123, v231
	v_fmac_f32_e32 v31, v124, v228
	v_fmac_f32_e32 v31, v125, v229
	v_fmac_f32_e32 v31, v126, v230
	v_fmac_f32_e32 v31, v127, v231
	v_fmac_f32_e32 v30, v128, v228
	v_fmac_f32_e32 v30, v129, v229
	v_fmac_f32_e32 v30, v130, v230
	v_fmac_f32_e32 v30, v131, v231
	v_fmac_f32_e32 v29, v132, v228
	v_fmac_f32_e32 v29, v133, v229
	v_fmac_f32_e32 v29, v134, v230
	v_fmac_f32_e32 v29, v135, v231
	v_fmac_f32_e32 v28, v136, v228
	v_fmac_f32_e32 v28, v137, v229
	v_fmac_f32_e32 v28, v138, v230
	v_fmac_f32_e32 v28, v139, v231
	v_fmac_f32_e32 v27, v140, v228
	v_fmac_f32_e32 v27, v141, v229
	v_fmac_f32_e32 v27, v142, v230
	v_fmac_f32_e32 v27, v143, v231
	v_fmac_f32_e32 v26, v144, v228
	v_fmac_f32_e32 v26, v145, v229
	v_fmac_f32_e32 v26, v146, v230
	v_fmac_f32_e32 v26, v147, v231
	v_fmac_f32_e32 v25, v148, v228
	v_fmac_f32_e32 v25, v149, v229
	v_fmac_f32_e32 v25, v150, v230
	v_fmac_f32_e32 v25, v151, v231
	v_fmac_f32_e32 v24, v152, v228
	v_fmac_f32_e32 v24, v153, v229
	v_fmac_f32_e32 v24, v154, v230
	v_fmac_f32_e32 v24, v155, v231
	v_fmac_f32_e32 v23, v156, v228
	v_fmac_f32_e32 v23, v157, v229
	v_fmac_f32_e32 v23, v158, v230
	v_fmac_f32_e32 v23, v159, v231
	s_waitcnt lgkmcnt(14)
	v_fmac_f32_e32 v22, v160, v228
	v_fmac_f32_e32 v22, v161, v229
	v_fmac_f32_e32 v22, v162, v230
	v_fmac_f32_e32 v22, v163, v231
	s_waitcnt lgkmcnt(13)
	v_fmac_f32_e32 v21, v164, v228
	v_fmac_f32_e32 v21, v165, v229
	v_fmac_f32_e32 v21, v166, v230
	v_fmac_f32_e32 v21, v167, v231
	s_waitcnt lgkmcnt(12)
	v_fmac_f32_e32 v20, v168, v228
	v_fmac_f32_e32 v20, v169, v229
	v_fmac_f32_e32 v20, v170, v230
	v_fmac_f32_e32 v20, v171, v231
	s_waitcnt lgkmcnt(11)
	v_fmac_f32_e32 v19, v172, v228
	v_fmac_f32_e32 v19, v173, v229
	v_fmac_f32_e32 v19, v174, v230
	v_fmac_f32_e32 v19, v175, v231
	s_waitcnt lgkmcnt(10)
	v_fmac_f32_e32 v18, v176, v228
	v_fmac_f32_e32 v18, v177, v229
	v_fmac_f32_e32 v18, v178, v230
	v_fmac_f32_e32 v18, v179, v231
	s_waitcnt lgkmcnt(9)
	v_fmac_f32_e32 v17, v182, v228
	v_fmac_f32_e32 v17, v183, v229
	v_fmac_f32_e32 v17, v184, v230
	v_fmac_f32_e32 v17, v185, v231
	s_waitcnt lgkmcnt(8)
	v_fmac_f32_e32 v16, v186, v228
	v_fmac_f32_e32 v16, v187, v229
	v_fmac_f32_e32 v16, v188, v230
	v_fmac_f32_e32 v16, v189, v231
	s_waitcnt lgkmcnt(7)
	v_fmac_f32_e32 v15, v190, v228
	v_fmac_f32_e32 v15, v191, v229
	v_fmac_f32_e32 v15, v192, v230
	v_fmac_f32_e32 v15, v193, v231
	s_waitcnt lgkmcnt(6)
	v_fmac_f32_e32 v14, v194, v228
	v_fmac_f32_e32 v14, v195, v229
	v_fmac_f32_e32 v14, v196, v230
	v_fmac_f32_e32 v14, v197, v231
	s_waitcnt lgkmcnt(5)
	v_fmac_f32_e32 v13, v198, v228
	v_fmac_f32_e32 v13, v199, v229
	v_fmac_f32_e32 v13, v200, v230
	v_fmac_f32_e32 v13, v201, v231
	s_waitcnt lgkmcnt(4)
	v_fmac_f32_e32 v12, v202, v228
	v_fmac_f32_e32 v12, v203, v229
	v_fmac_f32_e32 v12, v204, v230
	v_fmac_f32_e32 v12, v205, v231
	s_waitcnt lgkmcnt(3)
	v_fmac_f32_e32 v11, v206, v228
	v_fmac_f32_e32 v11, v207, v229
	v_fmac_f32_e32 v11, v208, v230
	v_fmac_f32_e32 v11, v209, v231
	s_waitcnt lgkmcnt(2)
	v_fmac_f32_e32 v10, v210, v228
	v_fmac_f32_e32 v10, v211, v229
	v_fmac_f32_e32 v10, v212, v230
	v_fmac_f32_e32 v10, v213, v231
	s_waitcnt lgkmcnt(1)
	v_fmac_f32_e32 v9, v214, v228
	v_fmac_f32_e32 v9, v215, v229
	v_fmac_f32_e32 v9, v216, v230
	v_fmac_f32_e32 v9, v217, v231
	s_waitcnt lgkmcnt(0)
	v_fmac_f32_e32 v8, v218, v228
	v_fmac_f32_e32 v8, v219, v229
	v_fmac_f32_e32 v8, v220, v230
	v_fmac_f32_e32 v8, v221, v231
	s_add_i32 s36, s36, 16
	s_cmp_gt_u32 s37, 59
	s_cbranch_scc0 .LBB0_128
	s_waitcnt lgkmcnt(0)
	s_movk_i32 s38, 0x200
	s_mov_b64 s[36:37], 0
	s_and_b64 vcc, exec, s[34:35]
	s_cbranch_vccz .LBB0_121
	s_load_dwordx2 s[30:31], s[26:27], 0x50
	s_barrier
	ds_write2st64_b32 v61, v47, v46 offset1:1
	ds_write2st64_b32 v61, v45, v44 offset0:2 offset1:3
	ds_write2st64_b32 v61, v43, v42 offset0:4 offset1:5
	ds_write2st64_b32 v61, v41, v40 offset0:6 offset1:7
	ds_write2st64_b32 v61, v39, v38 offset0:8 offset1:9
	ds_write2st64_b32 v61, v37, v36 offset0:10 offset1:11
	ds_write2st64_b32 v61, v35, v34 offset0:12 offset1:13
	ds_write2st64_b32 v61, v33, v32 offset0:14 offset1:15
	ds_write2st64_b32 v61, v31, v30 offset0:16 offset1:17
	ds_write2st64_b32 v61, v29, v28 offset0:18 offset1:19
	ds_write2st64_b32 v61, v27, v26 offset0:20 offset1:21
	ds_write2st64_b32 v61, v25, v24 offset0:22 offset1:23
	ds_write2st64_b32 v61, v23, v22 offset0:24 offset1:25
	ds_write2st64_b32 v61, v21, v20 offset0:26 offset1:27
	ds_write2st64_b32 v61, v19, v18 offset0:28 offset1:29
	ds_write2st64_b32 v61, v17, v16 offset0:30 offset1:31
	ds_write2st64_b32 v61, v15, v14 offset0:32 offset1:33
	ds_write2st64_b32 v61, v13, v12 offset0:34 offset1:35
	ds_write2st64_b32 v61, v11, v10 offset0:36 offset1:37
	ds_write2st64_b32 v61, v9, v8 offset0:38 offset1:39
	s_waitcnt lgkmcnt(0)
	s_barrier
	s_mul_i32 s35, s47, 0x3000
	s_mul_hi_i32 s34, s47, 0x3000
	v_mov_b32_e32 v12, v60
	v_mov_b32_e32 v13, v59
	s_waitcnt lgkmcnt(0)
	s_add_u32 s30, s30, s35
	s_addc_u32 s31, s31, s34
	s_add_u32 s30, s30, s28
	s_addc_u32 s31, s31, s29
	v_lshl_add_u64 v[8:9], s[30:31], 0, v[2:3]
	s_mul_i32 s31, s47, 0x78000
	s_mul_hi_i32 s30, s47, 0x78000
	s_add_u32 s28, s31, s28
	s_addc_u32 s29, s30, s29
	v_lshl_add_u64 v[10:11], v[6:7], 0, s[28:29]
	s_mov_b64 s[28:29], 0
	global_load_dword v20, v[8:9], off
	s_waitcnt vmcnt(0)
.LBB0_131:
	ds_read2st64_b32 v[14:15], v12 offset1:40
	ds_read2st64_b32 v[16:17], v12 offset0:80 offset1:120
	ds_read2st64_b32 v[18:19], v12 offset0:160 offset1:200
	v_add_u32_e32 v21, 0x11800, v12
	ds_read_b32 v22, v12 offset:61440
	ds_read_b32 v21, v21
	v_add_u32_e32 v13, 0x200, v13
	v_cmp_lt_u32_e32 vcc, s42, v13
	v_add_u32_e32 v12, 0x800, v12
	s_or_b64 s[28:29], vcc, s[28:29]
	s_waitcnt lgkmcnt(4)
	v_add_f32_e32 v14, v20, v14
	v_add_f32_e32 v14, v14, v15
	s_waitcnt lgkmcnt(3)
	v_add_f32_e32 v14, v14, v16
	v_add_f32_e32 v14, v14, v17
	s_waitcnt lgkmcnt(2)
	v_add_f32_e32 v14, v14, v18
	v_add_f32_e32 v14, v14, v19
	s_waitcnt lgkmcnt(1)
	v_add_f32_e32 v14, v14, v22
	s_waitcnt lgkmcnt(0)
	v_add_f32_e32 v14, v14, v21
	global_store_dword v[10:11], v14, off
	v_lshl_add_u64 v[10:11], v[10:11], 0, s[6:7]
	s_andn2_b64 exec, exec, s[28:29]
	s_cbranch_execnz .LBB0_131
	s_or_b64 exec, exec, s[28:29]
	s_add_i32 s15, s15, s13
	s_cmpk_gt_i32 s15, 0x5f
	s_barrier
	s_cbranch_scc0 .LBB0_120

.LBB0_525:
	v_and_b32_e32 v2, 64, v198
	v_xor_b32_e32 v1, 32, v198
	v_add_u32_e32 v2, 64, v2
	v_cmp_lt_i32_e32 vcc, v1, v2
	s_mulk_i32 s37, 0x2200
	v_lshrrev_b32_e32 v16, 3, v0
	v_cndmask_b32_e32 v1, v198, v1, vcc
	v_lshlrev_b32_e32 v1, 2, v1
	ds_bpermute_b32 v1, v1, v171
	v_lshlrev_b32_e32 v64, 11, v16
	v_or_b32_e32 v32, 0x4000, v64
	v_mov_b32_e32 v33, v65
	v_or_b32_e32 v34, 0x8000, v64
	s_waitcnt lgkmcnt(0)
	v_add_f32_e32 v1, v171, v1
	v_div_scale_f32 v2, s[2:3], v1, v1, 1.0
	v_rcp_f32_e32 v3, v2
	v_div_scale_f32 v4, vcc, 1.0, v1, 1.0
	s_add_i32 s2, s37, 0
	v_fma_f32 v5, -v2, v3, 1.0
	v_fmac_f32_e32 v3, v5, v3
	v_mul_f32_e32 v5, v4, v3
	v_fma_f32 v6, -v2, v5, v4
	v_fmac_f32_e32 v5, v6, v3
	v_fma_f32 v2, -v2, v5, v4
	v_div_fmas_f32 v2, v2, v3, v5
	v_div_fixup_f32 v6, v2, v1, 1.0
	v_mul_u32_u24_e32 v1, 0x110, v184
	v_pk_mul_f32 v[2:3], v[96:97], v[6:7] op_sel_hi:[1,0]
	v_pk_mul_f32 v[4:5], v[98:99], v[6:7] op_sel_hi:[1,0]
	v_add3_u32 v1, s2, v1, v170
	ds_write_b128 v1, v[2:5] offset:49152
	v_pk_mul_f32 v[2:3], v[100:101], v[6:7] op_sel_hi:[1,0]
	v_pk_mul_f32 v[4:5], v[102:103], v[6:7] op_sel_hi:[1,0]
	ds_write_b128 v1, v[2:5] offset:49184
	v_pk_mul_f32 v[2:3], v[104:105], v[6:7] op_sel_hi:[1,0]
	v_pk_mul_f32 v[4:5], v[106:107], v[6:7] op_sel_hi:[1,0]
	ds_write_b128 v1, v[2:5] offset:49216
	v_pk_mul_f32 v[2:3], v[108:109], v[6:7] op_sel_hi:[1,0]
	v_pk_mul_f32 v[4:5], v[110:111], v[6:7] op_sel_hi:[1,0]
	ds_write_b128 v1, v[2:5] offset:49248
	v_pk_mul_f32 v[2:3], v[80:81], v[6:7] op_sel_hi:[1,0]
	v_pk_mul_f32 v[4:5], v[82:83], v[6:7] op_sel_hi:[1,0]
	ds_write_b128 v1, v[2:5] offset:49280
	v_pk_mul_f32 v[2:3], v[84:85], v[6:7] op_sel_hi:[1,0]
	v_pk_mul_f32 v[4:5], v[86:87], v[6:7] op_sel_hi:[1,0]
	ds_write_b128 v1, v[2:5] offset:49312
	v_pk_mul_f32 v[2:3], v[88:89], v[6:7] op_sel_hi:[1,0]
	v_pk_mul_f32 v[4:5], v[90:91], v[6:7] op_sel_hi:[1,0]
	s_ashr_i32 s37, s36, 31
	ds_write_b128 v1, v[2:5] offset:49344
	v_pk_mul_f32 v[2:3], v[92:93], v[6:7] op_sel_hi:[1,0]
	v_pk_mul_f32 v[4:5], v[94:95], v[6:7] op_sel_hi:[1,0]
	s_lshl_b64 s[4:5], s[36:37], 10
	ds_write_b128 v1, v[2:5] offset:49376
	v_lshl_or_b32 v1, v169, 3, s4
	v_mov_b32_e32 v3, s5
	v_or_b32_e32 v2, s69, v1
	v_lshlrev_b64 v[12:13], 1, v[2:3]
	v_lshl_add_u64 v[14:15], s[16:17], 0, v[12:13]
	s_waitcnt lgkmcnt(0)
	v_lshl_add_u64 v[0:1], v[14:15], 0, v[64:65]
	s_nop 0
	v_lshl_add_u64 v[4:5], v[14:15], 0, v[32:33]
	s_nop 0
	v_mov_b32_e32 v35, v65
	v_lshl_add_u64 v[8:9], v[14:15], 0, v[34:35]
	s_nop 0
	v_lshl_add_u64 v[36:37], s[18:19], 0, v[12:13]
	v_lshl_add_u64 v[38:39], v[36:37], 0, v[64:65]
	v_or_b32_e32 v64, 0xc000, v64
	v_lshl_add_u64 v[12:13], v[14:15], 0, v[64:65]
	s_nop 0
	v_lshlrev_b32_e32 v17, 5, v169
	v_mul_u32_u24_e32 v16, 0x110, v16
	v_add3_u32 v48, s2, v17, v16
	ds_read_b128 v[16:19], v48 offset:49152
	ds_read_b128 v[20:23], v48 offset:49168
	ds_read_b128 v[24:27], v48 offset:51328
	ds_read_b128 v[28:31], v48 offset:51344
	s_waitcnt vmcnt(0)
	v_lshlrev_b32_e32 v40, 16, v210
	v_and_b32_e32 v41, 0xffff0000, v210
	v_lshlrev_b32_e32 v0, 16, v211
	v_and_b32_e32 v1, 0xffff0000, v211
	v_lshlrev_b32_e32 v42, 16, v212
	v_and_b32_e32 v43, 0xffff0000, v212
	v_lshlrev_b32_e32 v2, 16, v213
	v_and_b32_e32 v3, 0xffff0000, v213
	s_waitcnt lgkmcnt(3)
	v_pk_mul_f32 v[16:17], v[16:17], v[40:41]
	v_pk_mul_f32 v[18:19], v[18:19], v[0:1]
	s_waitcnt lgkmcnt(2)
	v_pk_mul_f32 v[20:21], v[20:21], v[42:43]
	v_pk_mul_f32 v[22:23], v[22:23], v[2:3]
	v_cvt_pk_bf16_f32 v0, v16, v17
	v_cvt_pk_bf16_f32 v1, v18, v19
	v_cvt_pk_bf16_f32 v2, v20, v21
	v_cvt_pk_bf16_f32 v3, v22, v23
	global_store_dwordx4 v[38:39], v[0:3], off
	s_nop 0
	v_lshlrev_b32_e32 v44, 16, v214
	v_and_b32_e32 v45, 0xffff0000, v214
	v_lshlrev_b32_e32 v0, 16, v217
	v_and_b32_e32 v1, 0xffff0000, v217
	v_lshlrev_b32_e32 v4, 16, v215
	v_and_b32_e32 v5, 0xffff0000, v215
	v_lshlrev_b32_e32 v46, 16, v216
	v_and_b32_e32 v47, 0xffff0000, v216
	s_waitcnt lgkmcnt(0)
	v_pk_mul_f32 v[0:1], v[30:31], v[0:1]
	v_pk_mul_f32 v[24:25], v[24:25], v[44:45]
	v_pk_mul_f32 v[26:27], v[26:27], v[4:5]
	v_pk_mul_f32 v[28:29], v[28:29], v[46:47]
	v_cvt_pk_bf16_f32 v7, v0, v1
	ds_read_b128 v[0:3], v48 offset:53504
	v_cvt_pk_bf16_f32 v4, v24, v25
	v_cvt_pk_bf16_f32 v5, v26, v27
	v_cvt_pk_bf16_f32 v6, v28, v29
	v_lshl_add_u64 v[16:17], v[36:37], 0, v[32:33]
	global_store_dwordx4 v[16:17], v[4:7], off
	ds_read_b128 v[4:7], v48 offset:53520
	s_nop 0
	v_lshlrev_b32_e32 v16, 16, v218
	v_and_b32_e32 v17, 0xffff0000, v218
	v_lshlrev_b32_e32 v8, 16, v219
	v_and_b32_e32 v9, 0xffff0000, v219
	s_waitcnt lgkmcnt(1)
	v_pk_mul_f32 v[0:1], v[0:1], v[16:17]
	v_pk_mul_f32 v[2:3], v[2:3], v[8:9]
	v_cvt_pk_bf16_f32 v0, v0, v1
	v_cvt_pk_bf16_f32 v1, v2, v3
	v_lshlrev_b32_e32 v2, 16, v220
	v_and_b32_e32 v3, 0xffff0000, v220
	s_waitcnt lgkmcnt(0)
	v_pk_mul_f32 v[2:3], v[4:5], v[2:3]
	v_lshlrev_b32_e32 v4, 16, v221
	v_and_b32_e32 v5, 0xffff0000, v221
	v_pk_mul_f32 v[4:5], v[6:7], v[4:5]
	v_cvt_pk_bf16_f32 v2, v2, v3
	v_cvt_pk_bf16_f32 v3, v4, v5
	ds_read_b128 v[4:7], v48 offset:55680
	v_lshl_add_u64 v[8:9], v[36:37], 0, v[34:35]
	global_store_dwordx4 v[8:9], v[0:3], off
	ds_read_b128 v[0:3], v48 offset:55696
	s_nop 0
	v_lshlrev_b32_e32 v8, 16, v222
	v_and_b32_e32 v9, 0xffff0000, v222
	s_waitcnt lgkmcnt(1)
	v_pk_mul_f32 v[4:5], v[4:5], v[8:9]
	v_lshlrev_b32_e32 v8, 16, v223
	v_and_b32_e32 v9, 0xffff0000, v223
	v_pk_mul_f32 v[6:7], v[6:7], v[8:9]
	v_cvt_pk_bf16_f32 v4, v4, v5
	v_cvt_pk_bf16_f32 v5, v6, v7
	v_lshlrev_b32_e32 v6, 16, v224
	v_and_b32_e32 v7, 0xffff0000, v224
	s_waitcnt lgkmcnt(0)
	v_pk_mul_f32 v[0:1], v[0:1], v[6:7]
	s_nop 0
	v_cvt_pk_bf16_f32 v6, v0, v1
	v_lshlrev_b32_e32 v0, 16, v225
	v_and_b32_e32 v1, 0xffff0000, v225
	v_pk_mul_f32 v[0:1], v[2:3], v[0:1]
	s_nop 0
	v_cvt_pk_bf16_f32 v7, v0, v1
	v_lshl_add_u64 v[0:1], v[36:37], 0, v[64:65]
	global_store_dwordx4 v[0:1], v[4:7], off
	s_waitcnt lgkmcnt(0)

.LBB0_538:
	v_mov_b32_e32 v168, v181
	s_and_b32 s28, s68, 15
	v_ashrrev_i32_e32 v1, 6, v168
	v_cmp_gt_i32_e32 vcc, s57, v168
	v_readfirstlane_b32 s37, v1
	s_and_saveexec_b64 s[2:3], vcc
	s_cbranch_execz .LBB0_542
	v_cmp_gt_i32_e32 vcc, s58, v168
	v_mov_b32_e32 v250, 0
	v_mov_b32_e32 v251, 0
	s_and_saveexec_b64 s[4:5], vcc
	s_cbranch_execz .LBB0_541
	s_mul_i32 s36, s28, 0x404
	s_add_u32 s38, s10, s36
	s_addc_u32 s39, s11, 0
	v_ashrrev_i32_e32 v169, 31, v168
	v_lshl_add_u64 v[2:3], v[168:169], 2, s[38:39]
	v_mov_b32_e32 v0, s36
	global_load_dword v250, v[2:3], off
	s_nop 0
	global_load_dword v251, v0, s[10:11] offset:1024

.LBB0_542:
	s_or_b64 exec, exec, s[2:3]
	s_lshl_b32 s46, s64, 2
	s_add_i32 s2, s46, -8
	s_cmp_gt_i32 s64, 2
	s_cselect_b32 s71, s2, 0
	s_lshl_b32 s2, s68, 7
	s_and_b32 s2, s2, 0xfffff800
	s_lshl_b32 s3, s64, 8
	s_add_i32 s4, s2, s3
	s_lshl_b32 s3, s71, 6
	s_add_i32 s40, s3, s2
	s_or_b32 s2, s46, 3
	s_ashr_i32 s72, s37, 1
	s_lshl_b32 s3, s37, 5
	s_sub_i32 s75, s2, s71
	s_lshl_b32 s2, s72, 6
	s_and_b32 s70, s3, 32
	s_or_b32 s5, s2, s70
	s_cmpk_lt_i32 s5, 0x100
	s_cselect_b64 s[38:39], -1, 0
	s_and_b64 s[2:3], s[38:39], exec
	s_cselect_b32 s2, s5, 0
	s_ashr_i32 s41, s40, 31
	v_and_b32_e32 v184, 31, v168
	s_add_i32 s36, s4, s2
	s_lshl_b32 s69, s28, 6
	s_lshl_b32 s28, s28, 7
	s_lshl_b64 s[4:5], s[40:41], 11
	v_or_b32_e32 v2, s36, v184
	s_add_u32 s2, s50, s4
	v_ashrrev_i32_e32 v3, 31, v2
	s_addc_u32 s3, s51, s5
	v_lshlrev_b64 v[2:3], 11, v[2:3]
	s_add_u32 s42, s2, s28
	v_bfe_u32 v0, v168, 5, 1
	v_lshl_add_u64 v[2:3], s[14:15], 0, v[2:3]
	s_addc_u32 s43, s3, 0
	s_min_i32 s2, s75, 0
	v_lshl_add_u64 v[2:3], v[2:3], 0, s[28:29]
	v_lshlrev_b32_e32 v170, 4, v0
	v_mov_b32_e32 v171, v65
	s_ashr_i32 s3, s2, 31
	v_lshl_add_u64 v[2:3], v[2:3], 0, v[170:171]
	v_and_b32_e32 v169, 7, v168
	v_mov_b32_e32 v78, v65
	v_mov_b32_e32 v79, v65
	s_lshl_b64 s[44:45], s[2:3], 17
	global_load_dwordx4 v[140:143], v[2:3], off
	global_load_dwordx4 v[136:139], v[2:3], off offset:32
	global_load_dwordx4 v[132:135], v[2:3], off offset:64
	global_load_dwordx4 v[128:131], v[2:3], off offset:96
	v_ashrrev_i32_e32 v4, 3, v168
	v_lshlrev_b32_e32 v186, 4, v169
	v_mov_b32_e32 v64, v65
	s_waitcnt vmcnt(6)
	v_mov_b32_e32 v66, v65
	v_mov_b32_e32 v67, v65
	v_mov_b32_e32 v68, v65
	v_mov_b32_e32 v69, v65
	v_mov_b32_e32 v70, v65
	v_mov_b32_e32 v71, v65
	v_mov_b32_e32 v72, v65
	v_mov_b32_e32 v73, v65
	v_mov_b32_e32 v74, v65
	v_mov_b32_e32 v75, v65
	v_mov_b32_e32 v76, v65
	v_mov_b32_e32 v77, v65
	v_mov_b64_e32 v[126:127], v[78:79]
	s_add_u32 s2, s42, s44
	v_lshl_or_b32 v0, v4, 11, v186
	v_mov_b64_e32 v[124:125], v[76:77]
	v_mov_b64_e32 v[122:123], v[74:75]
	v_mov_b64_e32 v[120:121], v[72:73]
	v_mov_b64_e32 v[118:119], v[70:71]
	v_mov_b64_e32 v[116:117], v[68:69]
	v_mov_b64_e32 v[114:115], v[66:67]
	v_mov_b64_e32 v[112:113], v[64:65]
	s_addc_u32 s3, s43, s45
	global_load_dwordx4 v[66:69], v0, s[2:3]
	v_lshlrev_b32_e32 v1, 2, v1
	v_and_b32_e32 v5, 12, v1
	v_and_b32_e32 v1, 60, v168
	v_and_b32_e32 v2, 3, v168
	v_lshlrev_b32_e32 v3, 1, v1
	v_cmp_gt_i32_e64 s[2:3], s54, v168
	s_and_saveexec_b64 s[42:43], s[2:3]
	s_cbranch_execz .LBB0_544
	s_lshl_b64 s[40:41], s[40:41], 10
	s_lshl_b64 s[40:41], s[40:41], 1
	s_add_u32 s40, s52, s40
	s_addc_u32 s41, s53, s41
	s_lshl_b32 s47, s69, 1
	s_add_u32 s40, s40, s47
	s_addc_u32 s41, s41, 0
	v_or_b32_e32 v6, v5, v2
	s_add_u32 s40, s40, s44
	v_lshl_or_b32 v64, v6, 13, v3
	s_addc_u32 s41, s41, s45
	v_lshl_add_u64 v[6:7], s[40:41], 0, v[64:65]
	v_lshl_add_u64 v[8:9], v[6:7], 0, s[30:31]
	v_add_co_u32_e32 v6, vcc, 0x1000, v6
	s_nop 1
	v_addc_co_u32_e32 v7, vcc, 0, v7, vcc
	global_load_dwordx2 v[172:173], v64, s[40:41]
	global_load_dwordx2 v[174:175], v64, s[40:41] offset:2048
	global_load_dwordx2 v[176:177], v[6:7], off
	global_load_dwordx2 v[178:179], v[8:9], off offset:2048
.LBB0_544:
	s_or_b64 exec, exec, s[42:43]
	v_cmp_gt_i32_e32 vcc, s57, v168
	s_and_saveexec_b64 s[40:41], vcc
	s_waitcnt vmcnt(5)
	v_sub_f32_e32 v250, v250, v251
	v_mul_f32_e32 v250, 0x3fb8aa3b, v250
	v_lshl_add_u32 v251, v168, 2, 0
	ds_write_b32 v251, v250 offset:47104
	s_or_b64 exec, exec, s[40:41]
	v_bfrev_b32_e32 v6, v168
	v_lshrrev_b32_e32 v6, 30, v6
	v_or_b32_e32 v5, v5, v6
	v_mul_lo_u32 v187, v4, s59
	v_add3_u32 v4, 0, v187, v186
	v_lshlrev_b32_e32 v188, 3, v5
	v_mul_u32_u24_e32 v189, 0x90, v1
	s_waitcnt vmcnt(0)
	ds_write_b128 v4, v[66:69]
	s_and_saveexec_b64 s[40:41], s[2:3]
	s_cbranch_execz .LBB0_546
	v_add3_u32 v1, 0, v188, v189
	v_perm_b32 v4, v174, v172, s60
	v_perm_b32 v5, v178, v176, s60
	v_perm_b32 v6, v174, v172, s61
	v_perm_b32 v7, v178, v176, s61
	v_add_u32_e32 v1, 0x2000, v1
	ds_write2_b64 v1, v[4:5], v[6:7] offset0:128 offset1:146
	v_perm_b32 v4, v175, v173, s60
	v_perm_b32 v5, v179, v177, s60
	v_perm_b32 v6, v175, v173, s61
	v_perm_b32 v7, v179, v177, s61
	ds_write2_b64 v1, v[4:5], v[6:7] offset0:164 offset1:182
.LBB0_546:
	s_or_b64 exec, exec, s[40:41]
	s_lshl_b32 s89, s36, 11
	s_add_u32 s90, s16, s89
	s_addc_u32 s91, s17, 0
	v_lshl_or_b32 v249, v169, 3, s69
	v_bfe_u32 v254, v168, 3, 3
	v_lshlrev_b32_e32 v249, 1, v249
	v_lshl_add_u32 v249, v254, 11, v249
	global_load_dwordx4 v[210:213], v249, s[90:91]
	s_add_u32 s90, s90, 0x4000
	s_addc_u32 s91, s91, 0
	global_load_dwordx4 v[214:217], v249, s[90:91]
	s_add_u32 s90, s90, 0x4000
	s_addc_u32 s91, s91, 0
	global_load_dwordx4 v[218:221], v249, s[90:91]
	s_add_u32 s90, s90, 0x4000
	s_addc_u32 s91, s91, 0
	global_load_dwordx4 v[222:225], v249, s[90:91]
	s_cmp_gt_u32 s75, 0x7ffffffe
	s_waitcnt lgkmcnt(0)
	s_barrier
	s_cbranch_scc1 .LBB0_577
	s_add_i32 s73, s72, s46
	s_add_i32 s75, s75, 1
	s_add_i32 s74, s73, -8
	s_or_b32 s4, s4, s28
	s_add_u32 s40, s8, s4
	v_mov_b32_e32 v1, v65
	s_addc_u32 s41, s9, s5
	s_sub_i32 s4, s73, s71
	s_and_b32 s5, s37, 1
	v_lshl_add_u64 v[182:183], v[0:1], 0, s[34:35]
	v_lshlrev_b32_e32 v0, 9, v168
	s_lshl_b32 s4, s4, 8
	s_lshl_b32 s5, s5, 7
	v_and_b32_e32 v0, 0x18000, v0
	v_lshlrev_b32_e32 v1, 13, v2
	s_or_b32 s4, s4, s5
	v_or3_b32 v64, v0, v1, v3
	v_lshl_or_b32 v0, v184, 2, s4
	v_mov_b32_e32 v94, v65
	v_mov_b32_e32 v95, v65
	v_mul_u32_u24_e32 v79, 0x90, v184
	s_sub_i32 s76, s46, s71
	v_sub_u32_e32 v0, v0, v170
	v_mov_b32_e32 v80, v65
	v_mov_b32_e32 v81, v65
	v_mov_b32_e32 v82, v65
	v_mov_b32_e32 v83, v65
	v_mov_b32_e32 v84, v65
	v_mov_b32_e32 v85, v65
	v_mov_b32_e32 v86, v65
	v_mov_b32_e32 v87, v65
	v_mov_b32_e32 v88, v65
	v_mov_b32_e32 v89, v65
	v_mov_b32_e32 v90, v65
	v_mov_b32_e32 v91, v65
	v_mov_b32_e32 v92, v65
	v_mov_b32_e32 v93, v65
	v_mov_b32_e32 v171, 0
	v_mov_b64_e32 v[110:111], v[94:95]
	v_add3_u32 v190, 0, v79, v170
	s_add_i32 s28, s76, 3
	v_add_u32_e32 v191, s62, v0
	s_mov_b32 s48, 0
	s_mov_b64 s[44:45], -1
	v_mov_b32_e32 v78, 0
	v_mov_b64_e32 v[108:109], v[92:93]
	v_mov_b64_e32 v[106:107], v[90:91]
	v_mov_b64_e32 v[104:105], v[88:89]
	v_mov_b64_e32 v[102:103], v[86:87]
	v_mov_b64_e32 v[100:101], v[84:85]
	v_mov_b64_e32 v[98:99], v[82:83]
	v_mov_b64_e32 v[96:97], v[80:81]
	v_mov_b32_e32 v0, 0
	v_mov_b32_e32 v1, v171
	v_mov_b32_e32 v2, v171
	v_mov_b32_e32 v3, v171
	v_mov_b32_e32 v4, v171
	v_mov_b32_e32 v5, v171
	v_mov_b32_e32 v6, v171
	v_mov_b32_e32 v7, v171
	v_mov_b32_e32 v8, v171
	v_mov_b32_e32 v9, v171
	v_mov_b32_e32 v10, v171
	v_mov_b32_e32 v11, v171
	v_mov_b32_e32 v12, v171
	v_mov_b32_e32 v13, v171
	v_mov_b32_e32 v14, v171
	v_mov_b32_e32 v15, v171
	v_mov_b32_e32 v16, v171
	v_mov_b32_e32 v17, v171
	v_mov_b32_e32 v18, v171
	v_mov_b32_e32 v19, v171
	v_mov_b32_e32 v20, v171
	v_mov_b32_e32 v21, v171
	v_mov_b32_e32 v22, v171
	v_mov_b32_e32 v23, v171
	v_mov_b32_e32 v24, v171
	v_mov_b32_e32 v25, v171
	v_mov_b32_e32 v26, v171
	v_mov_b32_e32 v27, v171
	v_mov_b32_e32 v28, v171
	v_mov_b32_e32 v29, v171
	v_mov_b32_e32 v30, v171
	v_mov_b32_e32 v31, v171
